# ten split barriers (one transpose round each) with the mid-slice generation sampling
# speedup vs baseline: 1.0074x; 1.0074x over previous
.LBB0_126:
	v_mov_b32_e32 v201, 0x24008
	ds_read_b32 v200, v201
	s_waitcnt lgkmcnt(0)
	s_cmp_lt_i32 s88, 1
	s_cbranch_scc0 .Lsl0_out
	s_cmp_gt_i32 s89, 0
	s_cbranch_scc0 .Lsl0_out
	s_load_dword s4, s[0:1], 0x120
	s_load_dwordx16 s[52:67], s[0:1], 0x0
	s_load_dwordx16 s[68:83], s[0:1], 0x80
	s_waitcnt lgkmcnt(0)
	s_add_u32 s98, s34, 0xed10500
	s_addc_u32 s99, s35, 0
	v_mov_b32_e32 v201, 0
	s_lshl_b32 s4, s4, 1
	s_mul_i32 s5, s4, 1
	s_lshl_b32 s33, s2, 1
	s_add_i32 s33, s33, s5
	s_cmp_eq_u32 s89, 18
	s_cselect_b32 s5, 2, 11
	s_mul_i32 s4, s4, s5
	s_min_u32 s4, s4, 0x15d0
	s_cmp_ge_i32 s33, s4
	s_cbranch_scc1 .Lsl0_out
	s_add_u32 s94, s34, 0x1da0000
	s_addc_u32 s95, s35, 0
	v_writelane_b32 v252, s90, 0
	s_add_u32 s4, s34, 0x7a0000
	s_addc_u32 s5, s35, 0
	v_writelane_b32 v252, s91, 1
	v_writelane_b32 v252, s4, 2
	v_lshrrev_b32_e32 v138, 8, v204
	v_and_b32_e32 v139, 0xff, v204
	v_writelane_b32 v252, s5, 3
	s_add_u32 s4, s34, 0x720000
	s_addc_u32 s5, s35, 0
	v_writelane_b32 v252, s4, 4
	v_mul_u32_u24_e32 v140, 0x12000, v138
	v_mov_b32_e32 v129, 0
	v_writelane_b32 v252, s5, 5
	s_add_u32 s4, s34, 0x520000
	s_addc_u32 s5, s35, 0
	s_add_u32 s90, s34, 0x4a0000
	s_addc_u32 s91, s35, 0
	s_add_u32 s96, s34, 0x440000
	s_addc_u32 s97, s35, 0
	s_add_u32 s16, s34, 0x28a0000
	s_addc_u32 s17, s35, 0
	s_add_u32 s18, s0, 0x120
	v_writelane_b32 v252, s4, 6
	s_addc_u32 s19, s1, 0
	s_movk_i32 s8, 0x104
	s_movk_i32 s9, 0xffe0
	s_movk_i32 s10, 0x6000
	s_movk_i32 s11, 0x400
	s_mov_b32 s12, 0xbfb8aa3b
	s_mov_b32 s13, 0x42ce8ed0
	s_mov_b32 s14, 0xc2b17218
	s_movk_i32 s15, 0x1800
	v_mov_b32_e32 v141, 0xfffffd40
	v_mov_b32_e32 v142, 0xb00000
	v_mov_b32_e32 v143, 0x580000
	v_mov_b32_e32 v144, 0x7f800000
	v_writelane_b32 v252, s5, 7
	s_branch .Lsl0_22

.LBB0_189:
	v_mov_b32_e32 v201, 0x24008
	ds_read_b32 v200, v201
	s_waitcnt lgkmcnt(0)
	s_cmp_lg_u32 s88, 0
	s_cbranch_scc1 .Lsl1_out
	s_cmp_lg_u32 s89, 18
	s_cbranch_scc1 .Lsl1_out
	s_load_dword s4, s[0:1], 0x120
	s_load_dwordx16 s[52:67], s[0:1], 0x0
	s_load_dwordx16 s[68:83], s[0:1], 0x80
	s_waitcnt lgkmcnt(0)
	s_add_u32 s98, s34, 0xed10500
	s_addc_u32 s99, s35, 0
	v_mov_b32_e32 v201, 0
	s_lshl_b32 s4, s4, 1
	s_mul_i32 s5, s4, 2
	s_lshl_b32 s33, s2, 1
	s_add_i32 s33, s33, s5
	s_mov_b32 s5, 3
	s_mul_i32 s4, s4, s5
	s_min_u32 s4, s4, 0x15d0
	s_cmp_ge_i32 s33, s4
	s_cbranch_scc1 .Lsl1_out
	s_add_u32 s94, s34, 0x1da0000
	s_addc_u32 s95, s35, 0
	v_writelane_b32 v252, s90, 0
	s_add_u32 s4, s34, 0x7a0000
	s_addc_u32 s5, s35, 0
	v_writelane_b32 v252, s91, 1
	v_writelane_b32 v252, s4, 2
	v_lshrrev_b32_e32 v138, 8, v204
	v_and_b32_e32 v139, 0xff, v204
	v_writelane_b32 v252, s5, 3
	s_add_u32 s4, s34, 0x720000
	s_addc_u32 s5, s35, 0
	v_writelane_b32 v252, s4, 4
	v_mul_u32_u24_e32 v140, 0x12000, v138
	v_mov_b32_e32 v129, 0
	v_writelane_b32 v252, s5, 5
	s_add_u32 s4, s34, 0x520000
	s_addc_u32 s5, s35, 0
	s_add_u32 s90, s34, 0x4a0000
	s_addc_u32 s91, s35, 0
	s_add_u32 s96, s34, 0x440000
	s_addc_u32 s97, s35, 0
	s_add_u32 s16, s34, 0x28a0000
	s_addc_u32 s17, s35, 0
	s_add_u32 s18, s0, 0x120
	v_writelane_b32 v252, s4, 6
	s_addc_u32 s19, s1, 0
	s_movk_i32 s8, 0x104
	s_movk_i32 s9, 0xffe0
	s_movk_i32 s10, 0x6000
	s_movk_i32 s11, 0x400
	s_mov_b32 s12, 0xbfb8aa3b
	s_mov_b32 s13, 0x42ce8ed0
	s_mov_b32 s14, 0xc2b17218
	s_movk_i32 s15, 0x1800
	v_mov_b32_e32 v141, 0xfffffd40
	v_mov_b32_e32 v142, 0xb00000
	v_mov_b32_e32 v143, 0x580000
	v_mov_b32_e32 v144, 0x7f800000
	v_writelane_b32 v252, s5, 7
	s_branch .Lsl1_22

.LBB0_1013:
	s_or_b64 exec, exec, s[4:5]
	s_waitcnt lgkmcnt(0)
	s_barrier
.LBB0_1014:
	v_mov_b32_e32 v201, 0x24008
	ds_read_b32 v200, v201
	s_waitcnt lgkmcnt(0)
	s_cmp_lg_u32 s88, 0
	s_cbranch_scc1 .Lsl6_out
	s_cmp_lg_u32 s89, 18
	s_cbranch_scc1 .Lsl6_out
	s_load_dword s4, s[0:1], 0x120
	s_load_dwordx16 s[52:67], s[0:1], 0x0
	s_load_dwordx16 s[68:83], s[0:1], 0x80
	s_waitcnt lgkmcnt(0)
	s_add_u32 s98, s34, 0xed10500
	s_addc_u32 s99, s35, 0
	v_mov_b32_e32 v201, 0
	s_lshl_b32 s4, s4, 1
	s_mul_i32 s5, s4, 6
	s_lshl_b32 s33, s2, 1
	s_add_i32 s33, s33, s5
	s_mov_b32 s5, 7
	s_mul_i32 s4, s4, s5
	s_min_u32 s4, s4, 0x15d0
	s_cmp_ge_i32 s33, s4
	s_cbranch_scc1 .Lsl6_out
	s_add_u32 s94, s34, 0x1da0000
	s_addc_u32 s95, s35, 0
	v_writelane_b32 v252, s90, 0
	s_add_u32 s4, s34, 0x7a0000
	s_addc_u32 s5, s35, 0
	v_writelane_b32 v252, s91, 1
	v_writelane_b32 v252, s4, 2
	v_lshrrev_b32_e32 v138, 8, v204
	v_and_b32_e32 v139, 0xff, v204
	v_writelane_b32 v252, s5, 3
	s_add_u32 s4, s34, 0x720000
	s_addc_u32 s5, s35, 0
	v_writelane_b32 v252, s4, 4
	v_mul_u32_u24_e32 v140, 0x12000, v138
	v_mov_b32_e32 v129, 0
	v_writelane_b32 v252, s5, 5
	s_add_u32 s4, s34, 0x520000
	s_addc_u32 s5, s35, 0
	s_add_u32 s90, s34, 0x4a0000
	s_addc_u32 s91, s35, 0
	s_add_u32 s96, s34, 0x440000
	s_addc_u32 s97, s35, 0
	s_add_u32 s16, s34, 0x28a0000
	s_addc_u32 s17, s35, 0
	s_add_u32 s18, s0, 0x120
	v_writelane_b32 v252, s4, 6
	s_addc_u32 s19, s1, 0
	s_movk_i32 s8, 0x104
	s_movk_i32 s9, 0xffe0
	s_movk_i32 s10, 0x6000
	s_movk_i32 s11, 0x400
	s_mov_b32 s12, 0xbfb8aa3b
	s_mov_b32 s13, 0x42ce8ed0
	s_mov_b32 s14, 0xc2b17218
	s_movk_i32 s15, 0x1800
	v_mov_b32_e32 v141, 0xfffffd40
	v_mov_b32_e32 v142, 0xb00000
	v_mov_b32_e32 v143, 0x580000
	v_mov_b32_e32 v144, 0x7f800000
	v_writelane_b32 v252, s5, 7
	s_branch .Lsl6_22

.Lsl10_out:
	s_cmp_gt_i32 s88, 10
	s_cbranch_scc1 .Lsb10_skip
	s_cmp_lt_i32 s89, 12
	s_cbranch_scc1 .Lsb10_skip
	s_waitcnt vmcnt(0) lgkmcnt(0)
	s_and_saveexec_b64 s[16:17], s[92:93]
	s_cbranch_execz .Lsb10_done
	v_mov_b32_e32 v0, 0x24008
	ds_read_b32 v1, v0
	buffer_inv sc1
	s_add_u32 s18, s34, 0xed10500
	s_addc_u32 s19, s35, 0
	v_mov_b32_e32 v0, 0
	s_mov_b32 s20, 0
	s_waitcnt lgkmcnt(0)
	v_cmp_eq_u32_e32 vcc, v200, v1
	s_cbranch_vccz .Lsb10_done
